# attention loop: per-tile scalar setup and branches moved in front of the barrier, first QK MFMA directly behind it, V fragment reads interleaved with QK MFMAs
# speedup vs baseline: 1.0211x; 1.0187x over previous
; #define LAS __attribute__((address_space(3)))
; #define PG8_WAIT_V(n) asm volatile("s_waitcnt vmcnt(" #n ")" ::: "memory")
; #define PG8_WAIT_L(n) asm volatile("s_waitcnt lgkmcnt(" #n ")" ::: "memory")
; #define PG8_BAR __builtin_amdgcn_s_barrier()
; #define PG8_SCHED __builtin_amdgcn_sched_barrier(0)
; #define MFMA32(a, b, c) __builtin_amdgcn_mfma_f32_32x32x16_bf16((a), (b), (c), 0, 0, 0)
; #define ATT_STAGE(t, ring) do { const int _so = (int)((size_t)(t) * inc); _Pragma("unroll") for (int _i = 0; _i < 4; ++_i) \
;     __builtin_amdgcn_raw_ptr_buffer_load_lds(srs, (LAS void*)(lds + stg_base + (ring) * 16384 + _i * 1024), 16, (int)soff[_i & 1], _so + (int)(_i * cstride), 0, 0); } while (0)
; DI void attn_item(const Params& p, const int item) {
;     ...
;   for (int t = 0; t < nT - 1; ++t) {
;     PG8_WAIT_L(0); PG8_WAIT_V(4); PG8_BAR;
;     { const int tk = t + 4 < nT ? t + 4 : nT - 1, tv = t + 2 < nT ? t + 2 : nT - 1; if (wid < 4) ATT_STAGE(tk, m1); else ATT_STAGE(tv, m2); }
;     const LAS unsigned char* vb = lds + m0 * 16384;
;     if ((t == tL && tL > 0) || t == tR) {
;       const float f = t == tR ? fR : fL;
; #pragma unroll
;       for (int db = 0; db < 4; ++db)
; #pragma unroll
;         for (int i = 0; i < 16; ++i) O[db][i] *= f;
;     }
;     bf16x8 vfA[4][2], vfB[4][2];
; #pragma unroll
;     for (int db = 0; db < 4; ++db)
; #pragma unroll
;       for (int s = 0; s < 2; ++s) vfA[db][s] = *(const LAS bf16x8*)(vb + db * 4096 + voff[s]);
;     ATT_QK(t + 1);
;     PG8_SCHED;
; #pragma unroll
;     for (int db = 0; db < 4; ++db)
; #pragma unroll
;       for (int s = 0; s < 2; ++s) vfB[db][s] = *(const LAS bf16x8*)(vb + db * 4096 + voff[s + 2]);
;     bf16x8 pfN[4];
; #pragma unroll
;     for (int s = 0; s < 2; ++s)
; #pragma unroll
;       for (int db = 0; db < 4; ++db) O[db] = MFMA32(vfA[db][s], pf[s], O[db]);
;     ATT_SM(0, pfN);
;     PG8_SCHED;
;     ATT_LDK(m2);
; #pragma unroll
;     for (int s = 0; s < 2; ++s)
; #pragma unroll
;       for (int db = 0; db < 4; ++db) O[db] = MFMA32(vfB[db][s], pf[s + 2], O[db]);
;     ATT_SM(1, pfN);
;     PG8_SCHED;
; #pragma unroll
;     for (int s = 0; s < 4; ++s) pf[s] = pfN[s];
;     { const int mm = m0; m0 = m1; m1 = m2; m2 = mm; }
.LBB0_987:
	s_mov_b32 s27, s25
	s_mov_b32 s25, s0
	s_and_b64 s[0:1], s[8:9], exec
	s_cselect_b32 s0, s27, s25
	s_add_i32 s1, s4, s28
	s_lshl_b32 s0, s0, 14
	s_min_u32 s1, s1, s20
	s_add_i32 s98, s18, s0
	s_mul_i32 s99, s1, s17
	s_lshl_b32 s1, s26, 14
	v_add_u32_e32 v241, s1, v228
	v_add_u32_e32 v242, s1, v227
	v_add_u32_e32 v234, s1, v226
	v_add_u32_e32 v235, s1, v225
	s_add_i32 s29, s28, 1
	s_cmp_lt_i32 s29, s19
	s_cselect_b64 s[34:35], -1, 0
	s_cmp_ge_u32 s29, s21
	s_cselect_b64 vcc, -1, 0
	s_or_b64 s[34:35], s[34:35], vcc
	s_cmp_eq_u32 s19, s28
	s_cselect_b64 s[0:1], -1, 0
	s_and_b64 s[30:31], s[10:11], s[0:1]
	s_cmp_eq_u32 s5, s24
	s_cselect_b64 s[0:1], -1, 0
	s_or_b64 s[30:31], s[30:31], s[0:1]
	s_cmp_eq_u32 s22, s24
	s_cselect_b64 s[100:101], -1, 0
	s_waitcnt lgkmcnt(0)
	s_waitcnt vmcnt(4)
	s_barrier
	s_and_b64 vcc, exec, s[30:31]
	s_cbranch_vccnz .Latt_rescale
.Latt_rescale_done:
	s_andn2_b64 vcc, exec, s[34:35]
	s_cbranch_vccnz .Latt_near
	v_mfma_f32_32x32x16_bf16 v[64:79], v[152:155], v[96:99], 0
	ds_read_b128 v[176:179], v241 offset:49152
	ds_read_b128 v[180:183], v241 offset:53248
	v_mfma_f32_32x32x16_bf16 v[80:95], v[156:159], v[96:99], 0
	ds_read_b128 v[172:175], v242 offset:49152
	ds_read_b128 v[168:171], v242 offset:53248
.LBB0_993:
	s_cmp_eq_u32 s23, s28
	s_cselect_b64 vcc, -1, 0
	s_mov_b32 m0, s98
	v_mfma_f32_32x32x16_bf16 v[64:79], v[148:151], v[100:103], v[64:79]
	buffer_load_dwordx4 v218, s[64:67], s99 offen lds
	ds_read_b128 v[184:187], v241 offset:57344
	ds_read_b128 v[188:191], v241 offset:61440
	v_mfma_f32_32x32x16_bf16 v[80:95], v[144:147], v[100:103], v[80:95]
	s_add_i32 m0, s98, 0x400
	s_add_i32 s99, s99, s7
	buffer_load_dwordx4 v219, s[64:67], s99 offen lds
	ds_read_b128 v[164:167], v242 offset:57344
	ds_read_b128 v[160:163], v242 offset:61440
	v_mfma_f32_32x32x16_bf16 v[64:79], v[140:143], v[104:107], v[64:79]
	v_mfma_f32_32x32x16_bf16 v[80:95], v[136:139], v[104:107], v[80:95]
	s_add_i32 m0, s98, 0x800
	s_add_i32 s99, s99, s7
	buffer_load_dwordx4 v218, s[64:67], s99 offen lds
	v_mfma_f32_32x32x16_bf16 v[64:79], v[132:135], v[108:111], v[64:79]
	v_mul_f32_e32 v233, v229, v231
	v_cndmask_b32_e32 v231, v231, v233, vcc
	v_mul_f32_e32 v233, v230, v231
	v_cndmask_b32_e64 v231, v231, v233, s[100:101]
	v_mfma_f32_32x32x16_bf16 v[80:95], v[128:131], v[108:111], v[80:95]
	s_add_i32 m0, s98, 0xc00
	s_add_i32 s99, s99, s7
	buffer_load_dwordx4 v219, s[64:67], s99 offen lds
	s_waitcnt lgkmcnt(7)
	v_mfma_f32_32x32x16_bf16 v[48:63], v[176:179], v[120:123], v[48:63]
	s_nop 2
	v_exp_f32_e32 v64, v64
	v_exp_f32_e32 v65, v65
	v_exp_f32_e32 v66, v66
	v_exp_f32_e32 v67, v67
	s_waitcnt lgkmcnt(6)
	v_mfma_f32_32x32x16_bf16 v[32:47], v[180:183], v[120:123], v[32:47]
	v_exp_f32_e32 v68, v68
	v_exp_f32_e32 v69, v69
	v_add_f32_e32 v231, v64, v231
	v_add_f32_e32 v231, v65, v231
	v_add_f32_e32 v231, v66, v231
	s_waitcnt lgkmcnt(3)
	v_mfma_f32_32x32x16_bf16 v[16:31], v[184:187], v[120:123], v[16:31]
	v_exp_f32_e32 v70, v70
	v_exp_f32_e32 v71, v71
	v_add_f32_e32 v231, v67, v231
	v_add_f32_e32 v231, v68, v231
	v_add_f32_e32 v231, v69, v231
	s_waitcnt lgkmcnt(2)
	v_mfma_f32_32x32x16_bf16 v[0:15], v[188:191], v[120:123], v[0:15]
	ds_read_b128 v[128:131], v234 offset:49152
	ds_read_b128 v[132:135], v234 offset:53248
	ds_read_b128 v[176:179], v235 offset:49152
	ds_read_b128 v[180:183], v235 offset:53248
	ds_read_b128 v[136:139], v234 offset:57344
	ds_read_b128 v[140:143], v234 offset:61440
	v_exp_f32_e32 v72, v72
	v_exp_f32_e32 v73, v73
	v_add_f32_e32 v231, v70, v231
	v_add_f32_e32 v231, v71, v231
	v_cvt_pk_bf16_f32 v120, v64, v65
	v_mfma_f32_32x32x16_bf16 v[48:63], v[172:175], v[112:115], v[48:63]
	ds_read_b128 v[172:175], v235 offset:57344
	ds_read_b128 v[184:187], v235 offset:61440
	v_exp_f32_e32 v74, v74
	v_exp_f32_e32 v75, v75
	v_add_f32_e32 v231, v72, v231
	v_add_f32_e32 v231, v73, v231
	v_cvt_pk_bf16_f32 v121, v66, v67
	v_mfma_f32_32x32x16_bf16 v[32:47], v[168:171], v[112:115], v[32:47]
	v_exp_f32_e32 v76, v76
	v_exp_f32_e32 v77, v77
	v_add_f32_e32 v231, v74, v231
	v_add_f32_e32 v231, v75, v231
	v_cvt_pk_bf16_f32 v122, v68, v69
	s_waitcnt lgkmcnt(9)
	v_mfma_f32_32x32x16_bf16 v[16:31], v[164:167], v[112:115], v[16:31]
	v_exp_f32_e32 v78, v78
	v_exp_f32_e32 v79, v79
	v_add_f32_e32 v231, v76, v231
	v_add_f32_e32 v231, v77, v231
	v_cvt_pk_bf16_f32 v123, v70, v71
	s_waitcnt lgkmcnt(8)
	v_mfma_f32_32x32x16_bf16 v[0:15], v[160:163], v[112:115], v[0:15]
	s_lshl_b32 s0, s25, 14
	v_add_u32_e32 v237, s0, v220
	v_exp_f32_e32 v80, v80
	v_exp_f32_e32 v81, v81
	v_add_f32_e32 v231, v78, v231
	v_add_f32_e32 v231, v79, v231
	v_cvt_pk_bf16_f32 v112, v72, v73
	s_waitcnt lgkmcnt(7)
	v_mfma_f32_32x32x16_bf16 v[48:63], v[128:131], v[124:127], v[48:63]
	v_add_u32_e32 v238, s0, v221
	v_add_u32_e32 v239, s0, v222
	v_add_u32_e32 v240, s0, v223
	v_exp_f32_e32 v82, v82
	v_exp_f32_e32 v83, v83
	v_add_f32_e32 v231, v80, v231
	v_add_f32_e32 v231, v81, v231
	v_cvt_pk_bf16_f32 v113, v74, v75
	s_waitcnt lgkmcnt(6)
	v_mfma_f32_32x32x16_bf16 v[32:47], v[132:135], v[124:127], v[32:47]
	v_exp_f32_e32 v84, v84
	v_exp_f32_e32 v85, v85
	v_add_f32_e32 v231, v82, v231
	v_add_f32_e32 v231, v83, v231
	v_cvt_pk_bf16_f32 v114, v76, v77
	s_waitcnt lgkmcnt(3)
	v_mfma_f32_32x32x16_bf16 v[16:31], v[136:139], v[124:127], v[16:31]
	v_exp_f32_e32 v86, v86
	v_exp_f32_e32 v87, v87
	v_add_f32_e32 v231, v84, v231
	v_add_f32_e32 v231, v85, v231
	v_cvt_pk_bf16_f32 v115, v78, v79
	s_waitcnt lgkmcnt(2)
	v_mfma_f32_32x32x16_bf16 v[0:15], v[140:143], v[124:127], v[0:15]
	ds_read_b128 v[152:155], v237
	ds_read_b128 v[156:159], v237 offset:4096
	ds_read_b128 v[148:151], v238
	ds_read_b128 v[144:147], v238 offset:4096
	ds_read_b128 v[140:143], v239
	ds_read_b128 v[136:139], v239 offset:4096
	ds_read_b128 v[132:135], v240
	ds_read_b128 v[128:131], v240 offset:4096
	v_exp_f32_e32 v88, v88
	v_exp_f32_e32 v89, v89
	v_add_f32_e32 v231, v86, v231
	v_add_f32_e32 v231, v87, v231
	v_cvt_pk_bf16_f32 v124, v80, v81
	v_mfma_f32_32x32x16_bf16 v[48:63], v[176:179], v[116:119], v[48:63]
	v_exp_f32_e32 v90, v90
	v_exp_f32_e32 v91, v91
	v_add_f32_e32 v231, v88, v231
	v_add_f32_e32 v231, v89, v231
	v_cvt_pk_bf16_f32 v125, v82, v83
	v_mfma_f32_32x32x16_bf16 v[32:47], v[180:183], v[116:119], v[32:47]
	v_exp_f32_e32 v92, v92
	v_exp_f32_e32 v93, v93
	v_add_f32_e32 v231, v90, v231
	v_add_f32_e32 v231, v91, v231
	v_cvt_pk_bf16_f32 v126, v84, v85
	s_waitcnt lgkmcnt(9)
	v_mfma_f32_32x32x16_bf16 v[16:31], v[172:175], v[116:119], v[16:31]
	v_exp_f32_e32 v94, v94
	v_exp_f32_e32 v95, v95
	v_add_f32_e32 v231, v92, v231
	v_add_f32_e32 v231, v93, v231
	v_cvt_pk_bf16_f32 v127, v86, v87
	s_waitcnt lgkmcnt(8)
	v_mfma_f32_32x32x16_bf16 v[0:15], v[184:187], v[116:119], v[0:15]
	v_add_f32_e32 v231, v94, v231
	v_add_f32_e32 v231, v95, v231
	v_cvt_pk_bf16_f32 v116, v88, v89
	v_cvt_pk_bf16_f32 v117, v90, v91
	v_cvt_pk_bf16_f32 v118, v92, v93
	v_cvt_pk_bf16_f32 v119, v94, v95
	s_add_i32 s24, s24, 64
	s_cmp_eq_u32 s20, s29
	s_cbranch_scc1 .LBB0_995
	s_mov_b32 s28, s29
	s_mov_b32 s0, s26
	s_mov_b32 s26, s27
	s_branch .LBB0_987
; DI void attn_item(const Params& p, const int item) {
;     ...
;     if ((t == tL && tL > 0) || t == tR) {
;       const float f = t == tR ? fR : fL;
; #pragma unroll
;       for (int db = 0; db < 4; ++db)
; #pragma unroll
;         for (int i = 0; i < 16; ++i) O[db][i] *= f;
;     }
.Latt_rescale:
	v_cndmask_b32_e64 v64, v229, v230, s[0:1]
	v_pk_mul_f32 v[62:63], v[62:63], v[64:65] op_sel_hi:[1,0]
	v_pk_mul_f32 v[60:61], v[60:61], v[64:65] op_sel_hi:[1,0]
	v_pk_mul_f32 v[58:59], v[58:59], v[64:65] op_sel_hi:[1,0]
	v_pk_mul_f32 v[56:57], v[56:57], v[64:65] op_sel_hi:[1,0]
	v_pk_mul_f32 v[54:55], v[54:55], v[64:65] op_sel_hi:[1,0]
	v_pk_mul_f32 v[52:53], v[52:53], v[64:65] op_sel_hi:[1,0]
	v_pk_mul_f32 v[50:51], v[50:51], v[64:65] op_sel_hi:[1,0]
	v_pk_mul_f32 v[48:49], v[48:49], v[64:65] op_sel_hi:[1,0]
	v_pk_mul_f32 v[46:47], v[46:47], v[64:65] op_sel_hi:[1,0]
	v_pk_mul_f32 v[44:45], v[44:45], v[64:65] op_sel_hi:[1,0]
	v_pk_mul_f32 v[42:43], v[42:43], v[64:65] op_sel_hi:[1,0]
	v_pk_mul_f32 v[40:41], v[40:41], v[64:65] op_sel_hi:[1,0]
	v_pk_mul_f32 v[38:39], v[38:39], v[64:65] op_sel_hi:[1,0]
	v_pk_mul_f32 v[36:37], v[36:37], v[64:65] op_sel_hi:[1,0]
	v_pk_mul_f32 v[34:35], v[34:35], v[64:65] op_sel_hi:[1,0]
	v_pk_mul_f32 v[32:33], v[32:33], v[64:65] op_sel_hi:[1,0]
	v_pk_mul_f32 v[30:31], v[30:31], v[64:65] op_sel_hi:[1,0]
	v_pk_mul_f32 v[28:29], v[28:29], v[64:65] op_sel_hi:[1,0]
	v_pk_mul_f32 v[26:27], v[26:27], v[64:65] op_sel_hi:[1,0]
	v_pk_mul_f32 v[24:25], v[24:25], v[64:65] op_sel_hi:[1,0]
	v_pk_mul_f32 v[22:23], v[22:23], v[64:65] op_sel_hi:[1,0]
	v_pk_mul_f32 v[20:21], v[20:21], v[64:65] op_sel_hi:[1,0]
	v_pk_mul_f32 v[18:19], v[18:19], v[64:65] op_sel_hi:[1,0]
	v_pk_mul_f32 v[16:17], v[16:17], v[64:65] op_sel_hi:[1,0]
	v_pk_mul_f32 v[14:15], v[14:15], v[64:65] op_sel_hi:[1,0]
	v_pk_mul_f32 v[12:13], v[12:13], v[64:65] op_sel_hi:[1,0]
	v_pk_mul_f32 v[10:11], v[10:11], v[64:65] op_sel_hi:[1,0]
	v_pk_mul_f32 v[8:9], v[8:9], v[64:65] op_sel_hi:[1,0]
	v_pk_mul_f32 v[6:7], v[6:7], v[64:65] op_sel_hi:[1,0]
	v_pk_mul_f32 v[4:5], v[4:5], v[64:65] op_sel_hi:[1,0]
	v_pk_mul_f32 v[2:3], v[2:3], v[64:65] op_sel_hi:[1,0]
	v_pk_mul_f32 v[0:1], v[0:1], v[64:65] op_sel_hi:[1,0]
	s_branch .Latt_rescale_done
.Latt_near:
	ds_read_b128 v[176:179], v241 offset:49152
	ds_read_b128 v[180:183], v241 offset:53248
	ds_read_b128 v[172:175], v242 offset:49152
	ds_read_b128 v[168:171], v242 offset:53248
	v_add_u32_e32 v88, s24, v224
	v_add_u32_e32 v64, 64, v88
	v_add_u32_e32 v65, 0x41, v88
	v_add_u32_e32 v66, 0x42, v88
	v_add_u32_e32 v67, 0x43, v88
	v_add_u32_e32 v68, 0x44, v88
	v_add_u32_e32 v69, 0x45, v88
	v_add_u32_e32 v70, 0x46, v88
	v_add_u32_e32 v71, 0x47, v88
	v_add_u32_e32 v72, 0x50, v88
	v_add_u32_e32 v73, 0x51, v88
	v_add_u32_e32 v74, 0x52, v88
	v_add_u32_e32 v75, 0x53, v88
	v_add_u32_e32 v76, 0x54, v88
	v_add_u32_e32 v77, 0x55, v88
	v_add_u32_e32 v78, 0x56, v88
	v_add_u32_e32 v79, 0x57, v88
	v_add_u32_e32 v80, 0x60, v88
	v_add_u32_e32 v81, 0x61, v88
	v_add_u32_e32 v82, 0x62, v88
	v_add_u32_e32 v83, 0x63, v88
	v_add_u32_e32 v84, 0x64, v88
	v_add_u32_e32 v85, 0x65, v88
	v_add_u32_e32 v86, 0x66, v88
	v_add_u32_e32 v87, 0x67, v88
	v_add_u32_e32 v89, 0x70, v88
	v_add_u32_e32 v90, 0x71, v88
	v_add_u32_e32 v91, 0x72, v88
	v_add_u32_e32 v92, 0x73, v88
	v_add_u32_e32 v93, 0x74, v88
	v_add_u32_e32 v94, 0x75, v88
	v_add_u32_e32 v95, 0x76, v88
	v_med3_i32 v64, v64, s87, v216
	s_add_i32 s0, 0, 0x20000
	v_med3_i32 v65, v65, s87, v216
	v_med3_i32 v66, v66, s87, v216
	v_med3_i32 v67, v67, s87, v216
	v_med3_i32 v68, v68, s87, v216
	v_med3_i32 v69, v69, s87, v216
	v_med3_i32 v70, v70, s87, v216
	v_med3_i32 v71, v71, s87, v216
	v_med3_i32 v72, v72, s87, v216
	v_med3_i32 v73, v73, s87, v216
	v_med3_i32 v74, v74, s87, v216
	v_med3_i32 v75, v75, s87, v216
	v_med3_i32 v76, v76, s87, v216
	v_med3_i32 v77, v77, s87, v216
	v_med3_i32 v78, v78, s87, v216
	v_med3_i32 v79, v79, s87, v216
	v_med3_i32 v80, v80, s87, v216
	v_med3_i32 v81, v81, s87, v216
	v_med3_i32 v82, v82, s87, v216
	v_med3_i32 v83, v83, s87, v216
	v_med3_i32 v84, v84, s87, v216
	v_med3_i32 v85, v85, s87, v216
	v_med3_i32 v86, v86, s87, v216
	v_med3_i32 v87, v87, s87, v216
	v_med3_i32 v89, v89, s87, v216
	v_med3_i32 v90, v90, s87, v216
	v_med3_i32 v91, v91, s87, v216
	v_med3_i32 v92, v92, s87, v216
	v_med3_i32 v93, v93, s87, v216
	v_med3_i32 v94, v94, s87, v216
	v_med3_i32 v95, v95, s87, v216
	v_add_u32_e32 v88, 0x77, v88
	v_lshl_add_u32 v64, v64, 2, s0
	v_lshl_add_u32 v65, v65, 2, s0
	v_lshl_add_u32 v66, v66, 2, s0
	v_lshl_add_u32 v67, v67, 2, s0
	v_lshl_add_u32 v68, v68, 2, s0
	v_lshl_add_u32 v69, v69, 2, s0
	v_lshl_add_u32 v70, v70, 2, s0
	v_lshl_add_u32 v71, v71, 2, s0
	v_lshl_add_u32 v72, v72, 2, s0
	v_lshl_add_u32 v73, v73, 2, s0
	v_lshl_add_u32 v74, v74, 2, s0
	v_lshl_add_u32 v75, v75, 2, s0
	v_lshl_add_u32 v76, v76, 2, s0
	v_lshl_add_u32 v77, v77, 2, s0
	v_lshl_add_u32 v78, v78, 2, s0
	v_lshl_add_u32 v79, v79, 2, s0
	v_lshl_add_u32 v80, v80, 2, s0
	v_lshl_add_u32 v81, v81, 2, s0
	v_lshl_add_u32 v82, v82, 2, s0
	v_lshl_add_u32 v83, v83, 2, s0
	v_lshl_add_u32 v84, v84, 2, s0
	v_lshl_add_u32 v85, v85, 2, s0
	v_lshl_add_u32 v86, v86, 2, s0
	v_lshl_add_u32 v87, v87, 2, s0
	v_lshl_add_u32 v89, v89, 2, s0
	v_lshl_add_u32 v90, v90, 2, s0
	v_lshl_add_u32 v91, v91, 2, s0
	v_lshl_add_u32 v92, v92, 2, s0
	v_lshl_add_u32 v93, v93, 2, s0
	v_lshl_add_u32 v94, v94, 2, s0
	v_lshl_add_u32 v95, v95, 2, s0
	v_med3_i32 v88, v88, s87, v216
	ds_read_b32 v64, v64 offset:512
	ds_read_b32 v65, v65 offset:512
	ds_read_b32 v66, v66 offset:512
	ds_read_b32 v67, v67 offset:512
	ds_read_b32 v68, v68 offset:512
	ds_read_b32 v69, v69 offset:512
	ds_read_b32 v70, v70 offset:512
	ds_read_b32 v71, v71 offset:512
	ds_read_b32 v72, v72 offset:512
	ds_read_b32 v73, v73 offset:512
	ds_read_b32 v74, v74 offset:512
	ds_read_b32 v75, v75 offset:512
	ds_read_b32 v76, v76 offset:512
	ds_read_b32 v77, v77 offset:512
	ds_read_b32 v78, v78 offset:512
	ds_read_b32 v79, v79 offset:512
	ds_read_b32 v80, v80 offset:512
	ds_read_b32 v81, v81 offset:512
	ds_read_b32 v82, v82 offset:512
	ds_read_b32 v83, v83 offset:512
	ds_read_b32 v84, v84 offset:512
	ds_read_b32 v85, v85 offset:512
	ds_read_b32 v86, v86 offset:512
	ds_read_b32 v87, v87 offset:512
	v_lshl_add_u32 v232, v88, 2, s0
	ds_read_b32 v88, v89 offset:512
	ds_read_b32 v89, v90 offset:512
	ds_read_b32 v90, v91 offset:512
	ds_read_b32 v91, v92 offset:512
	ds_read_b32 v92, v93 offset:512
	ds_read_b32 v93, v94 offset:512
	ds_read_b32 v94, v95 offset:512
	ds_read_b32 v95, v232 offset:512
	s_waitcnt lgkmcnt(14)
	v_mfma_f32_32x32x16_bf16 v[64:79], v[152:155], v[96:99], v[64:79]
	s_waitcnt lgkmcnt(0)
	v_mfma_f32_32x32x16_bf16 v[80:95], v[156:159], v[96:99], v[80:95]
	s_branch .LBB0_993

; __global__ void __launch_bounds__(512, 2) mega(Params p) {
	.amdhsa_kernel _Z4mega6Params
		.amdhsa_group_segment_fixed_size 0
		.amdhsa_private_segment_fixed_size 0
		.amdhsa_kernarg_size 392
		.amdhsa_user_sgpr_count 2
		.amdhsa_user_sgpr_dispatch_ptr 0
		.amdhsa_user_sgpr_queue_ptr 0
		.amdhsa_user_sgpr_kernarg_segment_ptr 1
		.amdhsa_user_sgpr_dispatch_id 0
		.amdhsa_user_sgpr_kernarg_preload_length 0
		.amdhsa_user_sgpr_kernarg_preload_offset 0
		.amdhsa_user_sgpr_private_segment_size 0
		.amdhsa_uses_dynamic_stack 0
		.amdhsa_enable_private_segment 0
		.amdhsa_system_sgpr_workgroup_id_x 1
		.amdhsa_system_sgpr_workgroup_id_y 0
		.amdhsa_system_sgpr_workgroup_id_z 0
		.amdhsa_system_sgpr_workgroup_info 0
		.amdhsa_system_vgpr_workitem_id 2
		.amdhsa_next_free_vgpr 243
		.amdhsa_next_free_sgpr 102
		.amdhsa_accum_offset 244
		.amdhsa_reserve_vcc 1
		.amdhsa_float_round_mode_32 0
		.amdhsa_float_round_mode_16_64 0
		.amdhsa_float_denorm_mode_32 3
		.amdhsa_float_denorm_mode_16_64 3
		.amdhsa_dx10_clamp 1
		.amdhsa_ieee_mode 1
		.amdhsa_fp16_overflow 0
		.amdhsa_tg_split 0
		.amdhsa_exception_fp_ieee_invalid_op 0
		.amdhsa_exception_fp_denorm_src 0
		.amdhsa_exception_fp_ieee_div_zero 0
		.amdhsa_exception_fp_ieee_overflow 0
		.amdhsa_exception_fp_ieee_underflow 0
		.amdhsa_exception_fp_ieee_inexact 0
		.amdhsa_exception_int_div_zero 0
	.end_amdhsa_kernel

; __global__ void __launch_bounds__(512, 2) mega(Params p) {
amdhsa.kernels:
  - .agpr_count:     0
    .args:
      - .offset:         0
        .size:           136
        .value_kind:     by_value
      - .offset:         136
        .size:           4
        .value_kind:     hidden_block_count_x
      - .offset:         140
        .size:           4
        .value_kind:     hidden_block_count_y
      - .offset:         144
        .size:           4
        .value_kind:     hidden_block_count_z
      - .offset:         148
        .size:           2
        .value_kind:     hidden_group_size_x
      - .offset:         150
        .size:           2
        .value_kind:     hidden_group_size_y
      - .offset:         152
        .size:           2
        .value_kind:     hidden_group_size_z
      - .offset:         154
        .size:           2
        .value_kind:     hidden_remainder_x
      - .offset:         156
        .size:           2
        .value_kind:     hidden_remainder_y
      - .offset:         158
        .size:           2
        .value_kind:     hidden_remainder_z
      - .offset:         176
        .size:           8
        .value_kind:     hidden_global_offset_x
      - .offset:         184
        .size:           8
        .value_kind:     hidden_global_offset_y
      - .offset:         192
        .size:           8
        .value_kind:     hidden_global_offset_z
      - .offset:         200
        .size:           2
        .value_kind:     hidden_grid_dims
      - .offset:         224
        .size:           8
        .value_kind:     hidden_multigrid_sync_arg
      - .offset:         256
        .size:           4
        .value_kind:     hidden_dynamic_lds_size
    .group_segment_fixed_size: 0
    .kernarg_segment_align: 8
    .kernarg_segment_size: 392
    .language:       OpenCL C
    .language_version:
      - 2
      - 0
    .max_flat_workgroup_size: 512
    .name:           _Z4mega6Params
    .private_segment_fixed_size: 0
    .sgpr_count:     108
    .sgpr_spill_count: 20
    .symbol:         _Z4mega6Params.kd
    .uniform_work_group_size: 1
    .uses_dynamic_stack: false
    .vgpr_count:     243
    .vgpr_spill_count: 0
    .wavefront_size: 64
